# E64: E52 plus counted lgkmcnt before each MFMA of the last P.V group (the one interleaved with the K/V staging ds_writes) in both diff-attention tile copies
# baseline (speedup 1.0000x reference)
; #define SBAR() __builtin_amdgcn_sched_barrier(0)
; template <int D0> __device__ __forceinline__ void pv_one_mi(f32x16& od, int vb, bf16x8 pa0, bf16x8 pa1, bf16x8 pa2, bf16x8 pa3, f32x16& q0) {
;   const s16x4 l0 = tr_read<v_rd_off(D0, 0, 0)>(vb), h0 = tr_read<v_rd_off(D0, 0, 1)>(vb), l1 = tr_read<v_rd_off(D0, 1, 0)>(vb), h1 = tr_read<v_rd_off(D0, 1, 1)>(vb);
;   const s16x4 l2 = tr_read<v_rd_off(D0, 2, 0)>(vb), h2 = tr_read<v_rd_off(D0, 2, 1)>(vb), l3 = tr_read<v_rd_off(D0, 3, 0)>(vb), h3 = tr_read<v_rd_off(D0, 3, 1)>(vb);
;   asm volatile("s_waitcnt lgkmcnt(0)" ::: "memory"); SBAR();
;     ...
;   od = __builtin_amdgcn_mfma_f32_32x32x16_bf16(pa0, PK(l0, h0), od, 0, 0, 0);
;   od = __builtin_amdgcn_mfma_f32_32x32x16_bf16(pa1, PK(l1, h1), od, 0, 0, 0);
;   od = __builtin_amdgcn_mfma_f32_32x32x16_bf16(pa2, PK(l2, h2), od, 0, 0, 0);
;   od = __builtin_amdgcn_mfma_f32_32x32x16_bf16(pa3, PK(l3, h3), od, 0, 0, 0);
;     ...
; #pragma unroll
;   for (int r = 4 * D0; r < 4 * D0 + 4; ++r) q0[r] = __builtin_amdgcn_exp2f(q0[r]);
.LBB0_1288:
	v_cvt_pk_bf16_f32 v232, v175, v176
	v_cvt_pk_bf16_f32 v233, v177, v178
	v_cvt_pk_bf16_f32 v234, v179, v181
	v_cvt_pk_bf16_f32 v235, v183, v185
	v_cvt_pk_bf16_f32 v236, v180, v182
	v_cvt_pk_bf16_f32 v237, v184, v227
	v_cvt_pk_bf16_f32 v238, v228, v229
	v_cvt_pk_bf16_f32 v239, v230, v174
	v_cvt_pk_bf16_f32 v228, v96, v97
	v_cvt_pk_bf16_f32 v229, v215, v99
	v_cvt_pk_bf16_f32 v230, v100, v101
	v_cvt_pk_bf16_f32 v231, v102, v103
	v_cvt_pk_bf16_f32 v96, v98, v104
	v_cvt_pk_bf16_f32 v97, v105, v106
	v_cvt_pk_bf16_f32 v98, v107, v108
	v_cvt_pk_bf16_f32 v99, v109, v110
	s_add_i32 s8, s13, 0xfffe8000
	s_add_i32 s9, s12, 0xfffe0000
	s_mov_b32 s38, s30
	s_mov_b32 s39, s31
	s_add_i32 s10, s13, 0xffff0000
	buffer_load_dwordx4 v[174:177], v216, s[28:31], s8 offen
	buffer_load_dwordx4 v[178:181], v216, s[28:31], s10 offen
	buffer_load_dwordx4 v[182:185], v217, s[36:39], s9 offen
	s_lshl_b32 s10, s58, 14
	v_add_u32_e32 v215, s10, v214
	ds_read_b64_tr_b16 v[100:101], v215 offset:0
	ds_read_b64_tr_b16 v[102:103], v215 offset:0x800
	ds_read_b64_tr_b16 v[104:105], v215 offset:0x1000
	ds_read_b64_tr_b16 v[106:107], v215 offset:0x1800
	ds_read_b64_tr_b16 v[108:109], v215 offset:0x2000
	ds_read_b64_tr_b16 v[110:111], v215 offset:0x2800
	ds_read_b64_tr_b16 v[240:241], v215 offset:0x3000
	ds_read_b64_tr_b16 v[242:243], v215 offset:0x3800
	s_waitcnt lgkmcnt(6)
	s_nop 0
	v_mfma_f32_32x32x16_bf16 v[0:15], v[232:235], v[100:103], v[0:15]
	ds_read_b64_tr_b16 v[100:101], v215 offset:0x200
	ds_read_b64_tr_b16 v[102:103], v215 offset:0xa00
	s_waitcnt lgkmcnt(6)
	v_mfma_f32_32x32x16_bf16 v[0:15], v[236:239], v[104:107], v[0:15]
	ds_read_b64_tr_b16 v[104:105], v215 offset:0x1200
	ds_read_b64_tr_b16 v[106:107], v215 offset:0x1a00
	s_waitcnt lgkmcnt(6)
	v_mfma_f32_32x32x16_bf16 v[0:15], v[228:231], v[108:111], v[0:15]
	ds_read_b64_tr_b16 v[108:109], v215 offset:0x2200
	ds_read_b64_tr_b16 v[110:111], v215 offset:0x2a00
	s_waitcnt lgkmcnt(6)
	v_mfma_f32_32x32x16_bf16 v[0:15], v[96:99], v[240:243], v[0:15]
	ds_read_b64_tr_b16 v[240:241], v215 offset:0x3200
	ds_read_b64_tr_b16 v[242:243], v215 offset:0x3a00
	s_waitcnt lgkmcnt(6)
	v_mfma_f32_32x32x16_bf16 v[48:63], v[232:235], v[100:103], v[48:63]
	ds_read_b64_tr_b16 v[100:101], v215 offset:0x400
	ds_read_b64_tr_b16 v[102:103], v215 offset:0xc00
	s_waitcnt lgkmcnt(6)
	v_mfma_f32_32x32x16_bf16 v[48:63], v[236:239], v[104:107], v[48:63]
	ds_read_b64_tr_b16 v[104:105], v215 offset:0x1400
	ds_read_b64_tr_b16 v[106:107], v215 offset:0x1c00
	s_waitcnt lgkmcnt(6)
	v_mfma_f32_32x32x16_bf16 v[48:63], v[228:231], v[108:111], v[48:63]
	ds_read_b64_tr_b16 v[108:109], v215 offset:0x2400
	ds_read_b64_tr_b16 v[110:111], v215 offset:0x2c00
	s_waitcnt lgkmcnt(6)
	v_mfma_f32_32x32x16_bf16 v[48:63], v[96:99], v[240:243], v[48:63]
	ds_read_b64_tr_b16 v[240:241], v215 offset:0x3400
	ds_read_b64_tr_b16 v[242:243], v215 offset:0x3c00
	s_waitcnt lgkmcnt(6)
	v_mfma_f32_32x32x16_bf16 v[32:47], v[232:235], v[100:103], v[32:47]
	ds_read_b64_tr_b16 v[100:101], v215 offset:0x600
	ds_read_b64_tr_b16 v[102:103], v215 offset:0xe00
	s_waitcnt lgkmcnt(6)
	v_mfma_f32_32x32x16_bf16 v[32:47], v[236:239], v[104:107], v[32:47]
	ds_read_b64_tr_b16 v[104:105], v215 offset:0x1600
	ds_read_b64_tr_b16 v[106:107], v215 offset:0x1e00
	s_waitcnt lgkmcnt(6)
	v_mfma_f32_32x32x16_bf16 v[32:47], v[228:231], v[108:111], v[32:47]
	ds_read_b64_tr_b16 v[108:109], v215 offset:0x2600
	ds_read_b64_tr_b16 v[110:111], v215 offset:0x2e00
	s_waitcnt lgkmcnt(6)
	v_mfma_f32_32x32x16_bf16 v[32:47], v[96:99], v[240:243], v[32:47]
	ds_read_b64_tr_b16 v[240:241], v215 offset:0x3600
	ds_read_b64_tr_b16 v[242:243], v215 offset:0x3e00
	s_waitcnt lgkmcnt(6)
	v_mfma_f32_32x32x16_bf16 v[16:31], v[232:235], v[100:103], v[16:31]
	s_waitcnt vmcnt(3)
	s_lshl_b32 s16, s59, 14
	v_add_u32_e32 v100, s16, v218
	s_mul_i32 s11, s59, 0x2400
	s_waitcnt vmcnt(5)
	ds_write_b128 v100, v[162:165]
	s_waitcnt vmcnt(4)
	ds_write_b128 v100, v[166:169] offset:8192
	v_add_u32_e32 v100, s11, v219
	v_cmp_gt_f32_e32 vcc, 1.0, v226
	s_waitcnt lgkmcnt(6)
	v_mfma_f32_32x32x16_bf16 v[16:31], v[236:239], v[104:107], v[16:31]
	s_waitcnt vmcnt(3)
	ds_write_b128 v100, v[170:173] offset:49152
	s_waitcnt lgkmcnt(5)
	v_mfma_f32_32x32x16_bf16 v[16:31], v[228:231], v[108:111], v[16:31]
	s_waitcnt lgkmcnt(3)
	v_mfma_f32_32x32x16_bf16 v[16:31], v[96:99], v[240:243], v[16:31]
	s_cbranch_vccz .LBB0_1292
	s_and_saveexec_b64 s[8:9], s[6:7]
	ds_write_b32 v199, v226 offset:128
	s_or_b64 exec, exec, s[8:9]
	s_waitcnt lgkmcnt(0)
	v_add_u32_e32 v108, v191, v198
	ds_read_b128 v[96:99], v108 offset:224
	ds_read_b128 v[100:103], v108 offset:192
	ds_read_b128 v[104:107], v108 offset:160
	ds_read_b128 v[108:111], v108 offset:128
	s_waitcnt lgkmcnt(3)
	v_pk_mul_f32 v[12:13], v[12:13], v[96:97]
	s_waitcnt lgkmcnt(2)
	v_pk_mul_f32 v[8:9], v[8:9], v[100:101]
	s_waitcnt lgkmcnt(1)
	v_pk_mul_f32 v[4:5], v[4:5], v[104:105]
	v_pk_mul_f32 v[14:15], v[14:15], v[98:99]
	v_pk_mul_f32 v[10:11], v[10:11], v[102:103]
	v_pk_mul_f32 v[6:7], v[6:7], v[106:107]
	s_waitcnt lgkmcnt(0)
	v_pk_mul_f32 v[2:3], v[2:3], v[110:111]
	v_pk_mul_f32 v[0:1], v[0:1], v[108:109]
	v_pk_mul_f32 v[60:61], v[60:61], v[96:97]
	v_pk_mul_f32 v[56:57], v[56:57], v[100:101]
	v_pk_mul_f32 v[52:53], v[52:53], v[104:105]
	v_pk_mul_f32 v[62:63], v[62:63], v[98:99]
	v_pk_mul_f32 v[58:59], v[58:59], v[102:103]
	v_pk_mul_f32 v[54:55], v[54:55], v[106:107]
	v_pk_mul_f32 v[50:51], v[50:51], v[110:111]
	v_pk_mul_f32 v[48:49], v[48:49], v[108:109]
	v_pk_mul_f32 v[44:45], v[44:45], v[96:97]
	v_pk_mul_f32 v[40:41], v[40:41], v[100:101]
	v_pk_mul_f32 v[36:37], v[36:37], v[104:105]
	v_pk_mul_f32 v[46:47], v[46:47], v[98:99]
	v_pk_mul_f32 v[42:43], v[42:43], v[102:103]
	v_pk_mul_f32 v[38:39], v[38:39], v[106:107]
	v_pk_mul_f32 v[34:35], v[34:35], v[110:111]
	v_pk_mul_f32 v[32:33], v[32:33], v[108:109]
	v_pk_mul_f32 v[28:29], v[28:29], v[96:97]
	v_pk_mul_f32 v[24:25], v[24:25], v[100:101]
	v_pk_mul_f32 v[20:21], v[20:21], v[104:105]
	v_pk_mul_f32 v[30:31], v[30:31], v[98:99]
	v_pk_mul_f32 v[26:27], v[26:27], v[102:103]
	v_pk_mul_f32 v[22:23], v[22:23], v[106:107]
	v_pk_mul_f32 v[18:19], v[18:19], v[110:111]
	v_pk_mul_f32 v[16:17], v[16:17], v[108:109]

; #define SBAR() __builtin_amdgcn_sched_barrier(0)
; template <int D0> __device__ __forceinline__ void pv_one_mi(f32x16& od, int vb, bf16x8 pa0, bf16x8 pa1, bf16x8 pa2, bf16x8 pa3, f32x16& q0) {
;   const s16x4 l0 = tr_read<v_rd_off(D0, 0, 0)>(vb), h0 = tr_read<v_rd_off(D0, 0, 1)>(vb), l1 = tr_read<v_rd_off(D0, 1, 0)>(vb), h1 = tr_read<v_rd_off(D0, 1, 1)>(vb);
;   const s16x4 l2 = tr_read<v_rd_off(D0, 2, 0)>(vb), h2 = tr_read<v_rd_off(D0, 2, 1)>(vb), l3 = tr_read<v_rd_off(D0, 3, 0)>(vb), h3 = tr_read<v_rd_off(D0, 3, 1)>(vb);
;   asm volatile("s_waitcnt lgkmcnt(0)" ::: "memory"); SBAR();
;     ...
;   od = __builtin_amdgcn_mfma_f32_32x32x16_bf16(pa0, PK(l0, h0), od, 0, 0, 0);
;   od = __builtin_amdgcn_mfma_f32_32x32x16_bf16(pa1, PK(l1, h1), od, 0, 0, 0);
;   od = __builtin_amdgcn_mfma_f32_32x32x16_bf16(pa2, PK(l2, h2), od, 0, 0, 0);
;   od = __builtin_amdgcn_mfma_f32_32x32x16_bf16(pa3, PK(l3, h3), od, 0, 0, 0);
;     ...
; #pragma unroll
;   for (int r = 4 * D0; r < 4 * D0 + 4; ++r) q0[r] = __builtin_amdgcn_exp2f(q0[r]);
.LBB0_1295:
	v_cvt_pk_bf16_f32 v250, v227, v229
	v_cvt_pk_bf16_f32 v251, v230, v233
	v_cvt_pk_bf16_f32 v252, v234, v237
	v_cvt_pk_bf16_f32 v253, v238, v241
	v_cvt_pk_bf16_f32 v228, v228, v231
	v_cvt_pk_bf16_f32 v229, v232, v235
	v_cvt_pk_bf16_f32 v230, v236, v239
	v_cvt_pk_bf16_f32 v231, v240, v242
	v_cvt_pk_bf16_f32 v232, v243, v244
	v_cvt_pk_bf16_f32 v233, v245, v115
	v_cvt_pk_bf16_f32 v234, v246, v247
	v_cvt_pk_bf16_f32 v235, v248, v119
	v_cvt_pk_bf16_f32 v116, v116, v117
	v_cvt_pk_bf16_f32 v117, v118, v120
	v_cvt_pk_bf16_f32 v118, v121, v122
	v_cvt_pk_bf16_f32 v119, v123, v124
	v_lshl_add_u32 v115, s15, 14, v214
	ds_read_b64_tr_b16 v[120:121], v115 offset:0
	ds_read_b64_tr_b16 v[122:123], v115 offset:0x800
	ds_read_b64_tr_b16 v[124:125], v115 offset:0x1000
	ds_read_b64_tr_b16 v[126:127], v115 offset:0x1800
	ds_read_b64_tr_b16 v[236:237], v115 offset:0x2000
	ds_read_b64_tr_b16 v[238:239], v115 offset:0x2800
	ds_read_b64_tr_b16 v[240:241], v115 offset:0x3000
	ds_read_b64_tr_b16 v[242:243], v115 offset:0x3800
	s_waitcnt lgkmcnt(6)
	s_nop 0
	v_mfma_f32_32x32x16_bf16 v[0:15], v[250:253], v[120:123], v[0:15]
	ds_read_b64_tr_b16 v[120:121], v115 offset:0x200
	ds_read_b64_tr_b16 v[122:123], v115 offset:0xa00
	s_waitcnt lgkmcnt(6)
	v_mfma_f32_32x32x16_bf16 v[0:15], v[228:231], v[124:127], v[0:15]
	ds_read_b64_tr_b16 v[124:125], v115 offset:0x1200
	ds_read_b64_tr_b16 v[126:127], v115 offset:0x1a00
	s_waitcnt lgkmcnt(6)
	v_mfma_f32_32x32x16_bf16 v[0:15], v[232:235], v[236:239], v[0:15]
	ds_read_b64_tr_b16 v[236:237], v115 offset:0x2200
	ds_read_b64_tr_b16 v[238:239], v115 offset:0x2a00
	s_waitcnt lgkmcnt(6)
	v_mfma_f32_32x32x16_bf16 v[0:15], v[116:119], v[240:243], v[0:15]
	ds_read_b64_tr_b16 v[240:241], v115 offset:0x3200
	ds_read_b64_tr_b16 v[242:243], v115 offset:0x3a00
	s_waitcnt lgkmcnt(6)
	v_mfma_f32_32x32x16_bf16 v[48:63], v[250:253], v[120:123], v[48:63]
	ds_read_b64_tr_b16 v[120:121], v115 offset:0x400
	ds_read_b64_tr_b16 v[122:123], v115 offset:0xc00
	s_waitcnt lgkmcnt(6)
	v_mfma_f32_32x32x16_bf16 v[48:63], v[228:231], v[124:127], v[48:63]
	ds_read_b64_tr_b16 v[124:125], v115 offset:0x1400
	ds_read_b64_tr_b16 v[126:127], v115 offset:0x1c00
	s_waitcnt lgkmcnt(6)
	v_mfma_f32_32x32x16_bf16 v[48:63], v[232:235], v[236:239], v[48:63]
	ds_read_b64_tr_b16 v[236:237], v115 offset:0x2400
	ds_read_b64_tr_b16 v[238:239], v115 offset:0x2c00
	s_waitcnt lgkmcnt(6)
	v_mfma_f32_32x32x16_bf16 v[48:63], v[116:119], v[240:243], v[48:63]
	ds_read_b64_tr_b16 v[240:241], v115 offset:0x3400
	ds_read_b64_tr_b16 v[242:243], v115 offset:0x3c00
	s_waitcnt lgkmcnt(6)
	v_mfma_f32_32x32x16_bf16 v[32:47], v[250:253], v[120:123], v[32:47]
	ds_read_b64_tr_b16 v[120:121], v115 offset:0x600
	ds_read_b64_tr_b16 v[122:123], v115 offset:0xe00
	s_waitcnt lgkmcnt(6)
	v_mfma_f32_32x32x16_bf16 v[32:47], v[228:231], v[124:127], v[32:47]
	ds_read_b64_tr_b16 v[124:125], v115 offset:0x1600
	ds_read_b64_tr_b16 v[126:127], v115 offset:0x1e00
	s_waitcnt lgkmcnt(6)
	v_mfma_f32_32x32x16_bf16 v[32:47], v[232:235], v[236:239], v[32:47]
	ds_read_b64_tr_b16 v[236:237], v115 offset:0x2600
	ds_read_b64_tr_b16 v[238:239], v115 offset:0x2e00
	s_waitcnt lgkmcnt(6)
	v_mfma_f32_32x32x16_bf16 v[32:47], v[116:119], v[240:243], v[32:47]
	ds_read_b64_tr_b16 v[240:241], v115 offset:0x3600
	ds_read_b64_tr_b16 v[242:243], v115 offset:0x3e00
	s_waitcnt lgkmcnt(6)
	v_mfma_f32_32x32x16_bf16 v[16:31], v[250:253], v[120:123], v[16:31]
	s_waitcnt vmcnt(3)
	v_add_u32_e32 v115, s10, v218
	s_mul_i32 s17, s58, 0x2400
	s_waitcnt vmcnt(2)
	ds_write_b128 v115, v[174:177]
	s_waitcnt vmcnt(1)
	ds_write_b128 v115, v[178:181] offset:8192
	v_add_u32_e32 v115, s17, v219
	v_cmp_gt_f32_e32 vcc, 1.0, v112
	s_waitcnt vmcnt(0)
	ds_write_b128 v115, v[182:185] offset:49152
	s_waitcnt lgkmcnt(7)
	v_mfma_f32_32x32x16_bf16 v[16:31], v[228:231], v[124:127], v[16:31]
	s_waitcnt lgkmcnt(5)
	v_mfma_f32_32x32x16_bf16 v[16:31], v[232:235], v[236:239], v[16:31]
	s_waitcnt lgkmcnt(3)
	v_mfma_f32_32x32x16_bf16 v[16:31], v[116:119], v[240:243], v[16:31]
	s_cbranch_vccz .LBB0_1299
	s_and_saveexec_b64 s[10:11], s[6:7]
	ds_write_b32 v199, v112 offset:128
	s_or_b64 exec, exec, s[10:11]
	s_waitcnt lgkmcnt(0)
	v_add_u32_e32 v115, v191, v198
	ds_read_b128 v[116:119], v115 offset:224
	ds_read_b128 v[120:123], v115 offset:192
	ds_read_b128 v[124:127], v115 offset:160
	ds_read_b128 v[174:177], v115 offset:128
	s_waitcnt lgkmcnt(3)
	v_pk_mul_f32 v[12:13], v[12:13], v[116:117]
	s_waitcnt lgkmcnt(2)
	v_pk_mul_f32 v[8:9], v[8:9], v[120:121]
	s_waitcnt lgkmcnt(1)
	v_pk_mul_f32 v[4:5], v[4:5], v[124:125]
	v_pk_mul_f32 v[14:15], v[14:15], v[118:119]
	v_pk_mul_f32 v[10:11], v[10:11], v[122:123]
	v_pk_mul_f32 v[6:7], v[6:7], v[126:127]
	s_waitcnt lgkmcnt(0)
	v_pk_mul_f32 v[2:3], v[2:3], v[176:177]
	v_pk_mul_f32 v[0:1], v[0:1], v[174:175]
	v_pk_mul_f32 v[60:61], v[60:61], v[116:117]
	v_pk_mul_f32 v[56:57], v[56:57], v[120:121]
	v_pk_mul_f32 v[52:53], v[52:53], v[124:125]
	v_pk_mul_f32 v[62:63], v[62:63], v[118:119]
	v_pk_mul_f32 v[58:59], v[58:59], v[122:123]
	v_pk_mul_f32 v[54:55], v[54:55], v[126:127]
	v_pk_mul_f32 v[50:51], v[50:51], v[176:177]
	v_pk_mul_f32 v[48:49], v[48:49], v[174:175]
	v_pk_mul_f32 v[44:45], v[44:45], v[116:117]
	v_pk_mul_f32 v[40:41], v[40:41], v[120:121]
	v_pk_mul_f32 v[36:37], v[36:37], v[124:125]
	v_pk_mul_f32 v[46:47], v[46:47], v[118:119]
	v_pk_mul_f32 v[42:43], v[42:43], v[122:123]
	v_pk_mul_f32 v[38:39], v[38:39], v[126:127]
	v_pk_mul_f32 v[34:35], v[34:35], v[176:177]
	v_pk_mul_f32 v[32:33], v[32:33], v[174:175]
	v_pk_mul_f32 v[28:29], v[28:29], v[116:117]
	v_pk_mul_f32 v[24:25], v[24:25], v[120:121]
	v_pk_mul_f32 v[20:21], v[20:21], v[124:125]
	v_pk_mul_f32 v[30:31], v[30:31], v[118:119]
	v_pk_mul_f32 v[26:27], v[26:27], v[122:123]
	v_pk_mul_f32 v[22:23], v[22:23], v[126:127]
	v_pk_mul_f32 v[18:19], v[18:19], v[176:177]
	v_pk_mul_f32 v[16:17], v[16:17], v[174:175]
